# retention: defer rh0 epilogue past next barrier, counted vmcnt
# baseline (speedup 1.0000x reference)
.LBB0_562:
	s_cmp_lt_i32 s84, 8
	s_cselect_b64 s[4:5], -1, 0
	s_cmp_gt_i32 s85, 7
	s_cselect_b64 s[6:7], -1, 0
	s_and_b64 s[4:5], s[4:5], s[6:7]
	s_andn2_b64 vcc, exec, s[4:5]
	s_cbranch_vccnz .LBB0_633
	s_mov_b64 s[4:5], s[70:71]
	s_mov_b64 s[6:7], s[70:71]
	s_mov_b64 s[8:9], s[70:71]
	s_mov_b64 s[10:11], s[70:71]
	s_mov_b64 s[12:13], s[70:71]
	s_cmpk_gt_i32 s72, 0xff
	s_cbranch_scc1 .LBB0_579
	s_load_dwordx2 s[26:27], s[4:5], 0xb8
	s_load_dwordx2 s[30:31], s[6:7], 0xb8
	s_load_dwordx2 s[36:37], s[8:9], 0xb8
	s_load_dwordx2 s[28:29], s[10:11], 0xb8
	s_load_dwordx2 s[34:35], s[12:13], 0xb8
	s_waitcnt lgkmcnt(0)
	s_add_u32 s10, s26, 0x20000000
	s_addc_u32 s11, s27, 0
	s_add_u32 s12, s30, 0x24000000
	s_addc_u32 s13, s31, 0
	s_add_u32 s22, s36, 0x2b000000
	s_addc_u32 s23, s37, 0
	s_lshr_b32 s4, s58, 8
	v_and_b32_e32 v2, 15, v0
	s_lshl_b32 s7, s4, 5
	s_movk_i32 s6, 0x210
	v_or_b32_e32 v6, s7, v2
	s_bfe_u32 s3, s58, 0x20006
	v_mul_lo_u32 v6, v6, s6
	s_add_i32 s14, 0, 0x10800
	v_lshrrev_b32_e32 v3, 4, v1
	s_lshl_b32 s5, s3, 4
	v_add_u32_e32 v10, 0, v6
	v_mov_b32_e32 v6, s14
	v_bfe_u32 v4, v0, 2, 2
	v_or_b32_e32 v5, s5, v2
	v_mad_u32_u24 v2, v2, s6, v6
	v_lshl_or_b32 v6, v3, 2, s7
	v_or_b32_e32 v7, v6, v4
	s_movk_i32 s7, 0x110
	v_mul_lo_u32 v7, v7, s7
	s_add_i32 s8, 0, 0x18c00
	v_lshlrev_b32_e32 v3, 3, v3
	v_lshrrev_b32_e32 v104, 3, v0
	v_add_u32_e32 v22, 1, v5
	v_add_u32_e32 v12, s8, v7
	v_lshlrev_b32_e32 v7, 3, v0
	v_or_b32_e32 v4, v3, v4
	v_cvt_f32_ubyte0_e32 v103, v22
	v_xor_b32_e32 v22, 63, v104
	v_and_b32_e32 v13, 24, v7
	v_mul_u32_u24_e32 v7, 0x210, v4
	v_cvt_f32_ubyte0_e32 v105, v22
	v_sub_u32_e32 v22, v5, v6
	v_add3_u32 v14, 0, v7, v13
	v_mov_b32_e32 v7, s8
	v_sub_u32_e32 v23, 0, v22
	v_mad_u32_u24 v15, v4, s7, v7
	v_mad_u32_u24 v20, v104, s7, v7
	v_bitop3_b32 v7, s5, v0, 15 bitop3:7
	v_max_i32_e32 v23, v22, v23
	v_add_u32_e32 v23, v23, v7
	v_xad_u32 v6, v6, -1, v5
	v_cvt_f32_i32_e32 v146, v23
	v_sub_u32_e32 v23, 0, v6
	v_max_i32_e32 v6, v6, v23
	v_add_u32_e32 v6, v6, v7
	v_cvt_f32_i32_e32 v147, v6
	v_add_u32_e32 v6, -2, v22
	v_sub_u32_e32 v23, 2, v22
	v_max_i32_e32 v6, v6, v23
	v_add_u32_e32 v6, v6, v7
	v_cvt_f32_i32_e32 v148, v6
	v_add_u32_e32 v6, -3, v22
	v_sub_u32_e32 v23, 3, v22
	v_max_i32_e32 v6, v6, v23
	v_add_u32_e32 v6, v6, v7
	v_cvt_f32_i32_e32 v149, v6
	v_add_u32_e32 v6, -16, v22
	v_sub_u32_e32 v23, 16, v22
	v_max_i32_e32 v6, v6, v23
	v_add_u32_e32 v6, v6, v7
	v_cvt_f32_i32_e32 v150, v6
	v_subrev_u32_e32 v6, 17, v22
	v_sub_u32_e32 v23, 17, v22
	v_max_i32_e32 v6, v6, v23
	v_add_u32_e32 v6, v6, v7
	v_cvt_f32_i32_e32 v151, v6
	v_subrev_u32_e32 v6, 18, v22
	v_sub_u32_e32 v23, 18, v22
	v_max_i32_e32 v6, v6, v23
	v_add_u32_e32 v6, v6, v7
	v_and_b32_e32 v9, 48, v0
	s_and_b32 s17, s58, 0xffffffc0
	v_and_b32_e32 v4, 7, v0
	v_cvt_f32_i32_e32 v152, v6
	v_subrev_u32_e32 v6, 19, v22
	v_sub_u32_e32 v22, 19, v22
	v_add_u32_e32 v11, v2, v9
	v_add_u32_e32 v16, s17, v2
	v_and_b32_e32 v2, 31, v0
	v_lshlrev_b32_e32 v21, 4, v4
	v_max_i32_e32 v6, v6, v22
	v_lshrrev_b32_e32 v102, 5, v0
	v_lshlrev_b32_e32 v19, 4, v2
	v_mov_b32_e32 v107, 0
	v_add_u32_e32 v6, v6, v7
	v_lshl_or_b32 v106, v104, 13, v21
	v_cvt_f32_i32_e32 v153, v6
	v_lshl_add_u64 v[6:7], s[36:37], 0, v[106:107]
	v_lshl_or_b32 v106, v102, 12, v19
	s_lshl_b32 s3, s3, 12
	v_lshl_add_u32 v155, v0, 4, s14
	s_mov_b64 s[14:15], 0x2b100000
	v_lshl_add_u64 v[110:111], s[26:27], 0, v[106:107]
	v_lshl_add_u64 v[112:113], s[30:31], 0, v[106:107]
	v_lshlrev_b32_e32 v106, 9, v5
	s_add_i32 s3, s3, 0
	v_lshl_add_u64 v[108:109], v[6:7], 0, s[14:15]
	v_lshl_add_u64 v[6:7], s[34:35], 0, v[106:107]
	s_mov_b64 s[14:15], 0x1b00000
	s_and_b32 s16, s58, 0xffffff00
	s_add_i32 s3, s3, 0x1d000
	v_lshl_add_u64 v[114:115], v[6:7], 0, s[14:15]
	v_lshrrev_b32_e32 v6, 1, v9
	v_lshlrev_b32_e32 v2, 3, v2
	s_cmp_eq_u32 s4, 1
	v_lshl_or_b32 v106, v5, 13, v6
	v_mad_u32_u24 v8, v5, s6, 0
	v_lshlrev_b32_e32 v17, 2, v1
	v_mad_u32_u24 v18, v102, s6, 0
	v_lshlrev_b32_e32 v4, 3, v4
	s_cselect_b64 s[4:5], -1, 0
	s_cmpk_lt_u32 s58, 0x100
	v_lshl_add_u64 v[6:7], s[28:29], 0, v[106:107]
	s_mov_b64 s[14:15], 0x3b000040
	v_lshlrev_b32_e32 v106, 1, v2
	v_mbcnt_lo_u32_b32 v2, -1, 0
	s_mov_b32 s25, 0
	s_cselect_b64 s[6:7], -1, 0
	v_cmp_gt_u32_e64 s[8:9], 16, v1
	v_or_b32_e32 v154, 0xfffffe00, v0
	v_lshl_add_u64 v[116:117], v[6:7], 0, s[14:15]
	s_mov_b32 s14, 0xc2fc0000
	s_mov_b32 s15, 0x800000
	s_movk_i32 s20, 0x63f
	s_mov_b32 s21, 0x10000
	s_mov_b32 s36, 0x20000
	s_mov_b32 s37, 0x30000
	v_lshlrev_b32_e32 v118, 1, v4
	s_mov_b32 s38, 0x40000
	s_mov_b32 s39, 0x50000
	s_mov_b32 s40, 0x60000
	s_mov_b32 s41, 0x70000
	s_mov_b32 s42, 0x80000
	v_add_u32_e32 v156, v8, v9
	v_add_u32_e32 v157, v10, v9
	v_add_u32_e32 v158, s16, v11
	v_add_u32_e32 v159, v12, v13
	v_add_u32_e32 v160, s17, v14
	v_add_u32_e32 v161, v15, v13
	v_add_u32_e32 v163, v16, v3
	s_mov_b64 s[26:27], 0x80000
	s_mov_b64 s[28:29], 0x8000
	v_mov_b32_e32 v164, 0x42800000
	v_mov_b32_e32 v165, 0x42000000
	v_mov_b32_e32 v172, v107
	v_mov_b32_e32 v173, v107
	v_mov_b32_e32 v174, v107
	v_mov_b32_e32 v175, v107
	v_not_b32_e32 v166, 63
	v_add_u32_e32 v167, v18, v19
	v_add_u32_e32 v168, v20, v21
	v_add_u32_e32 v169, s3, v17
	v_mbcnt_hi_u32_b32 v170, -1, v2
	v_xor_b32_e32 v240, 16, v170
	v_xor_b32_e32 v241, 32, v170
	v_lshlrev_b32_e32 v240, 2, v240
	v_lshlrev_b32_e32 v241, 2, v241
	s_mov_b32 s43, s72
	s_branch .LBB0_566
.LBB0_565:
	s_andn2_b64 vcc, exec, s[6:7]
	s_cbranch_vccnz .Lret_flush_skip
	v_cvt_pk_bf16_f32 v88, v220, v221
	v_cvt_pk_bf16_f32 v89, v222, v223
	v_add_f32_e32 v86, v220, v221
	v_mul_f32_e32 v87, v220, v220
	v_fmac_f32_e32 v87, v221, v221
	global_store_dwordx2 v[236:237], v[88:89], off offset:-64
	v_add_f32_e32 v86, v86, v222
	v_fmac_f32_e32 v87, v222, v222
	v_add_f32_e32 v86, v86, v223
	v_fmac_f32_e32 v87, v223, v223
	v_cvt_pk_bf16_f32 v90, v224, v225
	v_cvt_pk_bf16_f32 v91, v226, v227
	v_add_f32_e32 v86, v86, v224
	v_fmac_f32_e32 v87, v224, v224
	v_add_f32_e32 v86, v86, v225
	v_fmac_f32_e32 v87, v225, v225
	global_store_dwordx2 v[236:237], v[90:91], off offset:-32
	v_add_f32_e32 v86, v86, v226
	v_fmac_f32_e32 v87, v226, v226
	v_add_f32_e32 v86, v86, v227
	v_fmac_f32_e32 v87, v227, v227
	v_cvt_pk_bf16_f32 v92, v228, v229
	v_cvt_pk_bf16_f32 v93, v230, v231
	v_add_f32_e32 v86, v86, v228
	v_fmac_f32_e32 v87, v228, v228
	v_add_f32_e32 v86, v86, v229
	v_fmac_f32_e32 v87, v229, v229
	global_store_dwordx2 v[236:237], v[92:93], off
	v_add_f32_e32 v86, v86, v230
	v_fmac_f32_e32 v87, v230, v230
	v_add_f32_e32 v86, v86, v231
	v_fmac_f32_e32 v87, v231, v231
	v_cvt_pk_bf16_f32 v94, v232, v233
	v_cvt_pk_bf16_f32 v95, v234, v235
	v_add_f32_e32 v86, v86, v232
	v_fmac_f32_e32 v87, v232, v232
	v_add_f32_e32 v86, v86, v233
	v_fmac_f32_e32 v87, v233, v233
	global_store_dwordx2 v[236:237], v[94:95], off offset:32
	v_add_f32_e32 v86, v86, v234
	v_fmac_f32_e32 v87, v234, v234
	v_add_f32_e32 v86, v86, v235
	v_fmac_f32_e32 v87, v235, v235
	ds_bpermute_b32 v96, v240, v86
	ds_bpermute_b32 v97, v240, v87
	s_waitcnt lgkmcnt(0)
	v_add_f32_e32 v86, v86, v96
	v_add_f32_e32 v87, v87, v97
	ds_bpermute_b32 v96, v241, v86
	ds_bpermute_b32 v97, v241, v87
	s_waitcnt lgkmcnt(0)
	s_and_saveexec_b64 s[34:35], s[8:9]
	v_add_f32_e32 v86, v86, v96
	v_add_f32_e32 v87, v87, v97
	global_store_dwordx2 v[238:239], v[86:87], off
	s_or_b64 exec, exec, s[34:35]

.LBB0_570:
	s_waitcnt lgkmcnt(0)
	s_barrier
	s_cmp_eq_u32 s3, 0
	s_cbranch_scc1 .Lret_noepi
	s_andn2_b64 vcc, exec, s[6:7]
	s_cbranch_vccnz .Lret_noepi
	v_cvt_pk_bf16_f32 v88, v220, v221
	v_cvt_pk_bf16_f32 v89, v222, v223
	v_add_f32_e32 v86, v220, v221
	v_mul_f32_e32 v87, v220, v220
	v_fmac_f32_e32 v87, v221, v221
	global_store_dwordx2 v[236:237], v[88:89], off offset:-64
	v_add_f32_e32 v86, v86, v222
	v_fmac_f32_e32 v87, v222, v222
	v_add_f32_e32 v86, v86, v223
	v_fmac_f32_e32 v87, v223, v223
	v_cvt_pk_bf16_f32 v90, v224, v225
	v_cvt_pk_bf16_f32 v91, v226, v227
	v_add_f32_e32 v86, v86, v224
	v_fmac_f32_e32 v87, v224, v224
	v_add_f32_e32 v86, v86, v225
	v_fmac_f32_e32 v87, v225, v225
	global_store_dwordx2 v[236:237], v[90:91], off offset:-32
	v_add_f32_e32 v86, v86, v226
	v_fmac_f32_e32 v87, v226, v226
	v_add_f32_e32 v86, v86, v227
	v_fmac_f32_e32 v87, v227, v227
	v_cvt_pk_bf16_f32 v92, v228, v229
	v_cvt_pk_bf16_f32 v93, v230, v231
	v_add_f32_e32 v86, v86, v228
	v_fmac_f32_e32 v87, v228, v228
	v_add_f32_e32 v86, v86, v229
	v_fmac_f32_e32 v87, v229, v229
	global_store_dwordx2 v[236:237], v[92:93], off
	v_add_f32_e32 v86, v86, v230
	v_fmac_f32_e32 v87, v230, v230
	v_add_f32_e32 v86, v86, v231
	v_fmac_f32_e32 v87, v231, v231
	v_cvt_pk_bf16_f32 v94, v232, v233
	v_cvt_pk_bf16_f32 v95, v234, v235
	v_add_f32_e32 v86, v86, v232
	v_fmac_f32_e32 v87, v232, v232
	v_add_f32_e32 v86, v86, v233
	v_fmac_f32_e32 v87, v233, v233
	global_store_dwordx2 v[236:237], v[94:95], off offset:32
	v_add_f32_e32 v86, v86, v234
	v_fmac_f32_e32 v87, v234, v234
	v_add_f32_e32 v86, v86, v235
	v_fmac_f32_e32 v87, v235, v235
	ds_bpermute_b32 v96, v240, v86
	ds_bpermute_b32 v97, v240, v87
	s_waitcnt lgkmcnt(0)
	v_add_f32_e32 v86, v86, v96
	v_add_f32_e32 v87, v87, v97
	ds_bpermute_b32 v96, v241, v86
	ds_bpermute_b32 v97, v241, v87
	s_waitcnt lgkmcnt(0)
	s_and_saveexec_b64 s[34:35], s[8:9]
	v_add_f32_e32 v86, v86, v96
	v_add_f32_e32 v87, v87, v97
	global_store_dwordx2 v[238:239], v[86:87], off
	s_or_b64 exec, exec, s[34:35]
.Lret_noepi:
	ds_read_b128 v[86:89], v157 offset:33792
	ds_read_b128 v[90:93], v156
	ds_read_b128 v[94:97], v156 offset:64
	ds_read_b128 v[98:101], v157 offset:33856
	s_waitcnt lgkmcnt(2)
	v_mfma_f32_16x16x32_bf16 v[86:89], v[86:89], v[90:93], 0
	ds_read_b128 v[176:179], v157 offset:42240
	ds_read_b128 v[180:183], v157 offset:42304
	v_cndmask_b32_e64 v14, v14, v90, s[6:7]
	v_cndmask_b32_e64 v15, v15, v91, s[6:7]
	s_waitcnt lgkmcnt(2)
	v_mfma_f32_16x16x32_bf16 v[86:89], v[98:101], v[94:97], v[86:89]
	ds_read_b128 v[98:101], v157 offset:33920
	v_cndmask_b32_e64 v16, v16, v92, s[6:7]
	v_cndmask_b32_e64 v17, v17, v93, s[6:7]
	s_waitcnt lgkmcnt(2)
	v_mfma_f32_16x16x32_bf16 v[176:179], v[176:179], v[90:93], 0
	v_cndmask_b32_e64 v10, v10, v94, s[6:7]
	v_cndmask_b32_e64 v11, v11, v95, s[6:7]
	v_cndmask_b32_e64 v12, v12, v96, s[6:7]
	s_waitcnt lgkmcnt(1)
	v_mfma_f32_16x16x32_bf16 v[176:179], v[180:183], v[94:97], v[176:179]
	ds_read_b128 v[180:183], v156 offset:128
	ds_read_b128 v[184:187], v156 offset:192
	ds_read_b128 v[188:191], v157 offset:33984
	v_cndmask_b32_e64 v13, v13, v97, s[6:7]
	v_mov_b32_e32 v129, v128
	s_waitcnt lgkmcnt(2)
	v_mfma_f32_16x16x32_bf16 v[86:89], v[98:101], v[180:183], v[86:89]
	ds_read_b128 v[98:101], v157 offset:42368
	ds_read_b128 v[192:195], v157 offset:42432
	v_cndmask_b32_e64 v6, v6, v180, s[6:7]
	v_cndmask_b32_e64 v7, v7, v181, s[6:7]
	s_waitcnt lgkmcnt(1)
	v_mfma_f32_16x16x32_bf16 v[98:101], v[98:101], v[180:183], v[176:179]
	v_cndmask_b32_e64 v8, v8, v182, s[6:7]
	v_cndmask_b32_e64 v9, v9, v183, s[6:7]
	s_nop 0
	ds_read_b128 v[176:179], v157 offset:34048
	v_mfma_f32_16x16x32_bf16 v[86:89], v[188:191], v[184:187], v[86:89]
	v_cndmask_b32_e64 v2, v2, v184, s[6:7]
	v_cndmask_b32_e64 v3, v3, v185, s[6:7]
	v_cndmask_b32_e64 v4, v4, v186, s[6:7]
	s_waitcnt lgkmcnt(1)
	v_mfma_f32_16x16x32_bf16 v[98:101], v[192:195], v[184:187], v[98:101]
	ds_read_b128 v[188:191], v156 offset:256
	ds_read_b128 v[192:195], v156 offset:320
	ds_read_b128 v[196:199], v157 offset:34112
	v_cndmask_b32_e64 v5, v5, v187, s[6:7]
	v_pk_mul_f32 v[84:85], v[128:129], v[84:85]
	s_waitcnt lgkmcnt(2)
	v_mfma_f32_16x16x32_bf16 v[86:89], v[176:179], v[188:191], v[86:89]
	ds_read_b128 v[176:179], v157 offset:42496
	ds_read_b128 v[200:203], v157 offset:42560
	v_cndmask_b32_e64 v17, v17, v191, s[4:5]
	v_cndmask_b32_e64 v16, v16, v190, s[4:5]
	s_waitcnt lgkmcnt(1)
	v_mfma_f32_16x16x32_bf16 v[98:101], v[176:179], v[188:191], v[98:101]
	v_cndmask_b32_e64 v15, v15, v189, s[4:5]
	v_cndmask_b32_e64 v14, v14, v188, s[4:5]
	v_cndmask_b32_e64 v13, v13, v195, s[4:5]
	v_mfma_f32_16x16x32_bf16 v[86:89], v[196:199], v[192:195], v[86:89]
	ds_read_b128 v[176:179], v157 offset:34176
	ds_read_b128 v[196:199], v156 offset:384
	ds_read_b128 v[204:207], v157 offset:42624
	v_cndmask_b32_e64 v12, v12, v194, s[4:5]
	v_cndmask_b32_e64 v11, v11, v193, s[4:5]
	s_waitcnt lgkmcnt(3)
	v_mfma_f32_16x16x32_bf16 v[98:101], v[200:203], v[192:195], v[98:101]
	ds_read_b128 v[200:203], v156 offset:448
	ds_read_b128 v[208:211], v157 offset:34240
	ds_read_b128 v[90:93], v158
	v_cndmask_b32_e64 v10, v10, v192, s[4:5]
	s_waitcnt lgkmcnt(4)
	v_mfma_f32_16x16x32_bf16 v[86:89], v[176:179], v[196:199], v[86:89]
	ds_read_b128 v[176:179], v157 offset:42688
	v_cndmask_b32_e64 v9, v9, v199, s[4:5]
	v_cndmask_b32_e64 v8, v8, v198, s[4:5]
	s_waitcnt lgkmcnt(4)
	v_mfma_f32_16x16x32_bf16 v[98:101], v[204:207], v[196:199], v[98:101]
	ds_read_b128 v[204:207], v158 offset:8448
	v_cndmask_b32_e64 v7, v7, v197, s[4:5]
	v_cndmask_b32_e64 v6, v6, v196, s[4:5]
	s_waitcnt lgkmcnt(3)
	v_mfma_f32_16x16x32_bf16 v[86:89], v[208:211], v[200:203], v[86:89]
	v_cndmask_b32_e64 v5, v5, v203, s[4:5]
	v_cndmask_b32_e64 v4, v4, v202, s[4:5]
	v_cndmask_b32_e64 v3, v3, v201, s[4:5]
	s_waitcnt lgkmcnt(1)
	v_mfma_f32_16x16x32_bf16 v[98:101], v[176:179], v[200:203], v[98:101]
	ds_read_b128 v[176:179], v158 offset:16896
	ds_read_b128 v[188:191], v158 offset:64
	ds_read_b128 v[208:211], v158 offset:25344
	ds_read_b128 v[212:215], v158 offset:8512
	ds_read_b128 v[216:219], v158 offset:16960
	ds_read_b128 v[94:97], v158 offset:25408
	ds_read_b128 v[180:183], v158 offset:128
	ds_read_b128 v[192:195], v158 offset:8576
	v_mfma_f32_16x16x32_bf16 v[90:93], v[90:93], v[14:17], 0
	v_cndmask_b32_e64 v2, v2, v200, s[4:5]
	v_pk_mul_f32 v[86:87], v[120:121], v[86:87]
	v_pk_mul_f32 v[88:89], v[122:123], v[88:89]
	s_waitcnt lgkmcnt(8)
	v_mfma_f32_16x16x32_bf16 v[204:207], v[204:207], v[14:17], 0
	v_cvt_pk_bf16_f32 v86, v86, v87
	v_cvt_pk_bf16_f32 v87, v88, v89
	v_pk_mul_f32 v[88:89], v[124:125], v[98:99]
	s_waitcnt lgkmcnt(5)
	v_mfma_f32_16x16x32_bf16 v[208:211], v[208:211], v[14:17], 0
	v_mul_f32_e64 v98, v126, v100
	v_mul_f32_e64 v99, v127, v101
	v_cvt_pk_bf16_f32 v88, v88, v89
	v_cvt_pk_bf16_f32 v89, v98, v99
	v_mfma_f32_16x16x32_bf16 v[90:93], v[188:191], v[10:13], v[90:93]
	v_mul_f32_e64 v82, v134, v82
	v_mul_f32_e64 v83, v135, v83
	v_pk_mul_f32 v[80:81], v[128:129], v[80:81]
	v_pk_mul_f32 v[78:79], v[134:135], v[78:79]
	s_waitcnt lgkmcnt(4)
	v_mfma_f32_16x16x32_bf16 v[188:191], v[212:215], v[10:13], v[204:207]
	ds_read_b128 v[196:199], v158 offset:17024
	s_nop 1
	ds_read_b128 v[204:207], v158 offset:192
	v_pk_mul_f32 v[76:77], v[128:129], v[76:77]
	v_pk_mul_f32 v[74:75], v[134:135], v[74:75]
	v_mfma_f32_16x16x32_bf16 v[176:179], v[176:179], v[14:17], 0
	v_mul_f32_e64 v72, v128, v72
	v_mul_f32_e64 v73, v129, v73
	v_pk_mul_f32 v[70:71], v[134:135], v[70:71]
	v_pk_mul_f32 v[68:69], v[128:129], v[68:69]
	s_waitcnt lgkmcnt(4)
	v_mfma_f32_16x16x32_bf16 v[94:97], v[94:97], v[10:13], v[208:211]
	v_mul_f32_e64 v66, v134, v66
	v_mul_f32_e64 v67, v135, v67
	v_pk_mul_f32 v[64:65], v[128:129], v[64:65]
	v_pk_mul_f32 v[62:63], v[134:135], v[62:63]
	s_waitcnt lgkmcnt(3)
	v_mfma_f32_16x16x32_bf16 v[90:93], v[180:183], v[6:9], v[90:93]
	ds_read_b128 v[180:183], v158 offset:25472
	ds_read_b128 v[208:211], v158 offset:8640
	ds_read_b128 v[184:187], v158 offset:25536
	v_pk_mul_f32 v[60:61], v[128:129], v[60:61]
	s_waitcnt lgkmcnt(5)
	v_mfma_f32_16x16x32_bf16 v[188:191], v[192:195], v[6:9], v[188:191]
	ds_read_b128 v[192:195], v158 offset:17088
	v_pk_mul_f32 v[58:59], v[134:135], v[58:59]
	v_pk_mul_f32 v[56:57], v[128:129], v[56:57]
	v_mfma_f32_16x16x32_bf16 v[176:179], v[216:219], v[10:13], v[176:179]
	v_mul_f32_e64 v54, v134, v54
	v_mul_f32_e64 v55, v135, v55
	s_andn2_b64 vcc, exec, s[4:5]
	s_waitcnt lgkmcnt(5)
	v_mfma_f32_16x16x32_bf16 v[176:179], v[196:199], v[6:9], v[176:179]
	s_waitcnt lgkmcnt(3)
	v_mfma_f32_16x16x32_bf16 v[94:97], v[180:183], v[6:9], v[94:97]
	s_waitcnt lgkmcnt(2)
	v_mfma_f32_16x16x32_bf16 v[180:183], v[208:211], v[2:5], v[188:191]
	s_waitcnt lgkmcnt(0)
	v_mfma_f32_16x16x32_bf16 v[176:179], v[192:195], v[2:5], v[176:179]
	v_mfma_f32_16x16x32_bf16 v[184:187], v[184:187], v[2:5], v[94:97]
	s_nop 2
	ds_read_b64_tr_b16 v[96:97], v159 offset:4352
	ds_read_b64_tr_b16 v[94:95], v159
	ds_read_b64_tr_b16 v[190:191], v159 offset:4384
	ds_read_b64_tr_b16 v[188:189], v159 offset:32
	ds_read_b64_tr_b16 v[192:193], v159 offset:64
	ds_read_b64_tr_b16 v[196:197], v159 offset:96
	ds_read_b64_tr_b16 v[194:195], v159 offset:4416
	ds_read_b64_tr_b16 v[198:199], v159 offset:4448
	v_mfma_f32_16x16x32_bf16 v[90:93], v[204:207], v[2:5], v[90:93]
	s_waitcnt lgkmcnt(6)
	v_mfma_f32_16x16x32_bf16 v[98:101], v[94:97], v[86:89], v[90:93]
	s_waitcnt lgkmcnt(4)
	v_mfma_f32_16x16x32_bf16 v[94:97], v[188:191], v[86:89], v[180:183]
	s_waitcnt lgkmcnt(1)
	v_mfma_f32_16x16x32_bf16 v[90:93], v[192:195], v[86:89], v[176:179]
	s_waitcnt lgkmcnt(0)
	v_mfma_f32_16x16x32_bf16 v[86:89], v[196:199], v[86:89], v[184:187]
	s_nop 0
	ds_read_b64_tr_b16 v[178:179], v160 offset:35904
	ds_read_b64_tr_b16 v[176:177], v160 offset:33792
	ds_read_b64_tr_b16 v[182:183], v160 offset:35936
	ds_read_b64_tr_b16 v[180:181], v160 offset:33824
	ds_read_b64_tr_b16 v[186:187], v161 offset:1216
	ds_read_b64_tr_b16 v[184:185], v161 offset:128
	ds_read_b64_tr_b16 v[188:189], v161 offset:160
	ds_read_b64_tr_b16 v[192:193], v161 offset:192
	ds_read_b64_tr_b16 v[196:197], v161 offset:224
	ds_read_b64_tr_b16 v[190:191], v161 offset:1248
	ds_read_b64_tr_b16 v[194:195], v161 offset:1280
	ds_read_b64_tr_b16 v[198:199], v161 offset:1312
	s_waitcnt lgkmcnt(6)
	v_mfma_f32_16x16x32_bf16 v[82:85], v[176:179], v[184:187], v[82:85]
	s_waitcnt lgkmcnt(2)
	v_mfma_f32_16x16x32_bf16 v[78:81], v[176:179], v[188:191], v[78:81]
	s_waitcnt lgkmcnt(1)
	v_mfma_f32_16x16x32_bf16 v[74:77], v[176:179], v[192:195], v[74:77]
	s_waitcnt lgkmcnt(0)
	v_mfma_f32_16x16x32_bf16 v[70:73], v[176:179], v[196:199], v[70:73]
	v_mfma_f32_16x16x32_bf16 v[66:69], v[180:183], v[184:187], v[66:69]
	v_mfma_f32_16x16x32_bf16 v[62:65], v[180:183], v[188:191], v[62:65]
	v_mfma_f32_16x16x32_bf16 v[58:61], v[180:183], v[192:195], v[58:61]
	v_mfma_f32_16x16x32_bf16 v[54:57], v[180:183], v[196:199], v[54:57]
	ds_read_b64_tr_b16 v[176:177], v160 offset:50688
	ds_read_b64_tr_b16 v[178:179], v160 offset:52800
	ds_read_b64_tr_b16 v[182:183], v160 offset:52832
	ds_read_b64_tr_b16 v[180:181], v160 offset:50720
	ds_read_b64_tr_b16 v[186:187], v161 offset:9920
	ds_read_b64_tr_b16 v[184:185], v161 offset:8832
	ds_read_b64_tr_b16 v[188:189], v161 offset:8864
	ds_read_b64_tr_b16 v[192:193], v161 offset:8896
	ds_read_b64_tr_b16 v[196:197], v161 offset:8928
	ds_read_b64_tr_b16 v[190:191], v161 offset:9952
	ds_read_b64_tr_b16 v[194:195], v161 offset:9984
	ds_read_b64_tr_b16 v[198:199], v161 offset:10016
	s_waitcnt lgkmcnt(6)
	v_mfma_f32_16x16x32_bf16 v[82:85], v[176:179], v[184:187], v[82:85]
	s_waitcnt lgkmcnt(2)
	v_mfma_f32_16x16x32_bf16 v[78:81], v[176:179], v[188:191], v[78:81]
	s_waitcnt lgkmcnt(1)
	v_mfma_f32_16x16x32_bf16 v[74:77], v[176:179], v[192:195], v[74:77]
	s_waitcnt lgkmcnt(0)
	v_mfma_f32_16x16x32_bf16 v[70:73], v[176:179], v[196:199], v[70:73]
	v_mfma_f32_16x16x32_bf16 v[66:69], v[180:183], v[184:187], v[66:69]
	v_mfma_f32_16x16x32_bf16 v[62:65], v[180:183], v[188:191], v[62:65]
	v_mfma_f32_16x16x32_bf16 v[58:61], v[180:183], v[192:195], v[58:61]
	v_mfma_f32_16x16x32_bf16 v[54:57], v[180:183], v[196:199], v[54:57]
	s_cbranch_vccnz .LBB0_572
	ds_write2st64_b32 v169, v98, v99 offset1:1
	ds_write2st64_b32 v169, v100, v101 offset0:2 offset1:3
	ds_write2st64_b32 v169, v94, v95 offset0:4 offset1:5
	ds_write2st64_b32 v169, v96, v97 offset0:6 offset1:7
	ds_write2st64_b32 v169, v90, v91 offset0:8 offset1:9
	ds_write2st64_b32 v169, v92, v93 offset0:10 offset1:11
	ds_write2st64_b32 v169, v86, v87 offset0:12 offset1:13
	ds_write2st64_b32 v169, v88, v89 offset0:14 offset1:15
.LBB0_572:
	s_andn2_b64 vcc, exec, s[6:7]
	s_waitcnt lgkmcnt(0)
	s_barrier
	s_cbranch_vccnz .LBB0_576
	ds_read2st64_b32 v[176:177], v169 offset1:1
	ds_read2st64_b32 v[178:179], v169 offset0:2 offset1:3
	ds_read2st64_b32 v[180:181], v169 offset0:4 offset1:5
	ds_read2st64_b32 v[182:183], v169 offset0:6 offset1:7
	ds_read2st64_b32 v[184:185], v169 offset0:8 offset1:9
	ds_read2st64_b32 v[186:187], v169 offset0:10 offset1:11
	ds_read2st64_b32 v[188:189], v169 offset0:12 offset1:13
	ds_read2st64_b32 v[190:191], v169 offset0:14 offset1:15
	v_cvt_pk_bf16_f32 v192, v82, v83
	v_cvt_pk_bf16_f32 v193, v84, v85
	v_cvt_pk_bf16_f32 v194, v66, v67
	v_cvt_pk_bf16_f32 v195, v68, v69
	ds_write2_b64 v163, v[192:193], v[194:195] offset1:4
	v_cvt_pk_bf16_f32 v196, v78, v79
	v_cvt_pk_bf16_f32 v197, v80, v81
	v_cvt_pk_bf16_f32 v198, v62, v63
	v_cvt_pk_bf16_f32 v199, v64, v65
	v_add_u32_e32 v204, 0x2000, v163
	ds_write2_b64 v204, v[196:197], v[198:199] offset0:32 offset1:36
	v_cvt_pk_bf16_f32 v200, v74, v75
	v_cvt_pk_bf16_f32 v201, v76, v77
	v_cvt_pk_bf16_f32 v202, v58, v59
	v_cvt_pk_bf16_f32 v203, v60, v61
	v_add_u32_e32 v205, 0x4000, v163
	ds_write2_b64 v205, v[200:201], v[202:203] offset0:64 offset1:68
	v_cvt_pk_bf16_f32 v206, v70, v71
	v_cvt_pk_bf16_f32 v207, v72, v73
	v_cvt_pk_bf16_f32 v208, v54, v55
	v_cvt_pk_bf16_f32 v209, v56, v57
	v_add_u32_e32 v210, 0x6000, v163
	ds_write2_b64 v210, v[206:207], v[208:209] offset0:96 offset1:100
	s_waitcnt lgkmcnt(4)
	v_pk_add_f32 v[220:221], v[98:99], v[176:177]
	v_pk_add_f32 v[222:223], v[100:101], v[178:179]
	v_pk_add_f32 v[224:225], v[94:95], v[180:181]
	v_pk_add_f32 v[226:227], v[96:97], v[182:183]
	v_pk_add_f32 v[228:229], v[90:91], v[184:185]
	v_pk_add_f32 v[230:231], v[92:93], v[186:187]
	v_pk_add_f32 v[232:233], v[86:87], v[188:189]
	v_pk_add_f32 v[234:235], v[88:89], v[190:191]
	v_pk_mul_f32 v[220:221], v[130:131], v[220:221]
	v_pk_mul_f32 v[222:223], v[130:131], v[222:223]
	v_pk_mul_f32 v[224:225], v[130:131], v[224:225]
	v_pk_mul_f32 v[226:227], v[130:131], v[226:227]
	v_pk_mul_f32 v[228:229], v[130:131], v[228:229]
	v_pk_mul_f32 v[230:231], v[130:131], v[230:231]
	v_pk_mul_f32 v[232:233], v[130:131], v[232:233]
	v_pk_mul_f32 v[234:235], v[130:131], v[234:235]
	v_mov_b32_e32 v236, v144
	v_mov_b32_e32 v237, v145
	v_mov_b32_e32 v238, v142
	v_mov_b32_e32 v239, v143
	s_cmp_eq_u32 s30, 0xfc0000
	s_cbranch_scc1 .LBB0_569
	s_cmp_eq_u32 s3, 0
	s_cbranch_scc1 .Lret_vm0
	s_waitcnt vmcnt(5)
	s_branch .Lret_vmdone
.LBB0_576:
	v_cvt_pk_bf16_f32 v86, v82, v83
	v_cvt_pk_bf16_f32 v87, v84, v85
	v_cvt_pk_bf16_f32 v94, v66, v67
	v_cvt_pk_bf16_f32 v95, v68, v69
	s_waitcnt lgkmcnt(1)
	v_cvt_pk_bf16_f32 v88, v78, v79
	s_waitcnt lgkmcnt(0)
	v_cvt_pk_bf16_f32 v89, v80, v81
	ds_write2_b64 v163, v[86:87], v[94:95] offset1:4
	v_cvt_pk_bf16_f32 v86, v62, v63
	v_cvt_pk_bf16_f32 v87, v64, v65
	v_add_u32_e32 v94, 0x2000, v163
	v_cvt_pk_bf16_f32 v90, v74, v75
	v_cvt_pk_bf16_f32 v91, v76, v77
	ds_write2_b64 v94, v[88:89], v[86:87] offset0:32 offset1:36
	v_cvt_pk_bf16_f32 v86, v58, v59
	v_cvt_pk_bf16_f32 v87, v60, v61
	v_add_u32_e32 v88, 0x4000, v163
	v_cvt_pk_bf16_f32 v92, v70, v71
	v_cvt_pk_bf16_f32 v93, v72, v73
	ds_write2_b64 v88, v[90:91], v[86:87] offset0:64 offset1:68
	v_cvt_pk_bf16_f32 v86, v54, v55
	v_cvt_pk_bf16_f32 v87, v56, v57
	v_add_u32_e32 v88, 0x6000, v163
	s_cmp_eq_u32 s30, 0xfc0000
	ds_write2_b64 v88, v[92:93], v[86:87] offset0:96 offset1:100
	s_cbranch_scc1 .LBB0_569
.Lret_vm0:
	s_waitcnt vmcnt(0)
.Lret_vmdone:
	v_lshlrev_b32_e32 v86, 16, v50
	v_and_b32_e32 v87, 0xffff0000, v50
	v_lshlrev_b32_e32 v88, 16, v51
	v_and_b32_e32 v89, 0xffff0000, v51
	v_pk_mul_f32 v[86:87], v[132:133], v[86:87]
	v_pk_mul_f32 v[88:89], v[132:133], v[88:89]
	v_cvt_pk_bf16_f32 v86, v86, v87
	v_cvt_pk_bf16_f32 v87, v88, v89
	v_lshlrev_b32_e32 v88, 16, v52
	v_and_b32_e32 v89, 0xffff0000, v52
	v_lshlrev_b32_e32 v90, 16, v53
	v_and_b32_e32 v91, 0xffff0000, v53
	v_pk_mul_f32 v[88:89], v[132:133], v[88:89]
	v_pk_mul_f32 v[90:91], v[132:133], v[90:91]
	v_cvt_pk_bf16_f32 v88, v88, v89
	v_cvt_pk_bf16_f32 v89, v90, v91
	s_cmp_gt_u32 s3, 61
	ds_write_b128 v167, v[18:21]
	ds_write_b128 v167, v[22:25] offset:33792
	ds_write_b128 v167, v[26:29] offset:8448
	ds_write_b128 v167, v[30:33] offset:42240
	ds_write_b128 v167, v[34:37] offset:16896
	ds_write_b128 v167, v[38:41] offset:50688
	ds_write_b128 v167, v[42:45] offset:25344
	ds_write_b128 v167, v[46:49] offset:59136
	ds_write_b128 v168, v[50:53]
	ds_write_b128 v168, v[86:89] offset:128
	s_cbranch_scc1 .LBB0_569
	v_lshl_add_u64 v[42:43], v[138:139], 0, s[30:31]
	v_add_co_u32_e32 v18, vcc, 0x20080000, v42
	v_lshl_add_u64 v[46:47], v[140:141], 0, s[30:31]
	s_nop 0
	v_addc_co_u32_e32 v19, vcc, 0, v43, vcc
	v_add_co_u32_e32 v22, vcc, 0x24080000, v46
	global_load_dwordx4 v[18:21], v[18:19], off
	s_nop 0
	v_addc_co_u32_e32 v23, vcc, 0, v47, vcc
	v_add_co_u32_e32 v26, vcc, 0x20090000, v42
	global_load_dwordx4 v[22:25], v[22:23], off
	s_nop 0
	v_addc_co_u32_e32 v27, vcc, 0, v43, vcc
	v_add_co_u32_e32 v30, vcc, 0x24090000, v46
	global_load_dwordx4 v[26:29], v[26:27], off
	s_nop 0
	v_addc_co_u32_e32 v31, vcc, 0, v47, vcc
	v_add_co_u32_e32 v34, vcc, 0x200a0000, v42
	global_load_dwordx4 v[30:33], v[30:31], off
	s_nop 0
	v_addc_co_u32_e32 v35, vcc, 0, v43, vcc
	v_add_co_u32_e32 v38, vcc, 0x240a0000, v46
	global_load_dwordx4 v[34:37], v[34:35], off
	s_nop 0
	v_addc_co_u32_e32 v39, vcc, 0, v47, vcc
	v_add_co_u32_e32 v42, vcc, 0x200b0000, v42
	global_load_dwordx4 v[38:41], v[38:39], off
	s_nop 0
	v_addc_co_u32_e32 v43, vcc, 0, v43, vcc
	v_add_co_u32_e32 v46, vcc, 0x240b0000, v46
	global_load_dwordx4 v[42:45], v[42:43], off
	s_nop 0
	v_addc_co_u32_e32 v47, vcc, 0, v47, vcc
	global_load_dwordx4 v[46:49], v[46:47], off
	s_nop 0
	global_load_dwordx4 v[50:53], v[136:137], off
	s_branch .LBB0_569
